# v026 + grid barrier leader tail: no XGEN bump (nobody reads it since the non-leaders spin on TOPGEN), leader's acquire done before the last XCD's TOPGEN release and the release atomic not waited for:
# speedup vs baseline: 1.0016x; 1.0016x over previous
; __device__ __forceinline__ unsigned xb_ld(unsigned* p)              { return __hip_atomic_load(p, __ATOMIC_RELAXED, __HIP_MEMORY_SCOPE_AGENT); }
; __device__ __forceinline__ unsigned xb_add(unsigned* p, unsigned v) { return __hip_atomic_fetch_add(p, v, __ATOMIC_RELAXED, __HIP_MEMORY_SCOPE_AGENT); }
; #define XB_SPIN(cond, bar) do { unsigned _sp = 0; while (cond) { __builtin_amdgcn_s_sleep(1); \
;     if ((++_sp & 255u) == 0u) { if (xb_ld(&(bar)[XB_TMO])) break; if (_sp > XB_SPIN_CAP) { atomicAdd(&(bar)[XB_TMO], 1u); break; } } } } while (0)
; __device__ __forceinline__ void xcd_barrier(const XcdBarrier& b) {
;     ...
;         const unsigned old = xb_add(&bar[XB_XSUB(b.x)], 1u);
;         const unsigned gen = old / nloc;
;         if (old + 1u == (gen + 1u) * nloc) {
;             __builtin_amdgcn_fence(__ATOMIC_RELEASE, "agent");
;             asm volatile("s_waitcnt vmcnt(0)" ::: "memory");
;             const unsigned og = xb_add(&bar[XB_TOP], 1u);
;             const unsigned tg = og / nx;
;             if (og + 1u == (tg + 1u) * nx) xb_add(&bar[XB_TOPGEN], 1u);
;             else XB_SPIN(xb_ld(&bar[XB_TOPGEN]) == tg, bar);
;             __builtin_amdgcn_fence(__ATOMIC_ACQUIRE, "agent");
;             xb_add(&bar[XB_XGEN(b.x)], 1u);
;             asm volatile("s_waitcnt vmcnt(0)" ::: "memory");
;         } else {
;             XB_SPIN(xb_ld(&bar[XB_XGEN(b.x)]) == gen, bar);
;             __builtin_amdgcn_fence(__ATOMIC_ACQUIRE, "agent");
;             asm volatile("s_waitcnt vmcnt(0)" ::: "memory");
;         }
.LBB0_199:
	s_or_b64 exec, exec, s[6:7]
	buffer_inv sc1
	s_waitcnt vmcnt(0)
	s_and_saveexec_b64 s[6:7], s[10:11]
	s_cbranch_execz .LBB0_201
	v_mov_b32_e32 v2, 1
	global_atomic_add v[0:1], v2, off
.LBB0_201:
	s_or_b64 exec, exec, s[6:7]
.LBB0_204:
	s_or_b64 exec, exec, s[2:3]
	s_waitcnt lgkmcnt(0)
	s_barrier

; __device__ __forceinline__ unsigned xb_ld(unsigned* p)              { return __hip_atomic_load(p, __ATOMIC_RELAXED, __HIP_MEMORY_SCOPE_AGENT); }
; __device__ __forceinline__ unsigned xb_add(unsigned* p, unsigned v) { return __hip_atomic_fetch_add(p, v, __ATOMIC_RELAXED, __HIP_MEMORY_SCOPE_AGENT); }
; #define XB_SPIN(cond, bar) do { unsigned _sp = 0; while (cond) { __builtin_amdgcn_s_sleep(1); \
;     if ((++_sp & 255u) == 0u) { if (xb_ld(&(bar)[XB_TMO])) break; if (_sp > XB_SPIN_CAP) { atomicAdd(&(bar)[XB_TMO], 1u); break; } } } } while (0)
; __device__ __forceinline__ void xcd_barrier(const XcdBarrier& b) {
;     ...
;             if (og + 1u == (tg + 1u) * nx) xb_add(&bar[XB_TOPGEN], 1u);
;             else XB_SPIN(xb_ld(&bar[XB_TOPGEN]) == tg, bar);
;             __builtin_amdgcn_fence(__ATOMIC_ACQUIRE, "agent");
;             xb_add(&bar[XB_XGEN(b.x)], 1u);
;             asm volatile("s_waitcnt vmcnt(0)" ::: "memory");
.LBB0_272:
	s_or_b64 exec, exec, s[6:7]
.LBB0_275:
	s_or_b64 exec, exec, s[2:3]
	s_waitcnt lgkmcnt(0)
	s_barrier

; __device__ __forceinline__ unsigned xb_ld(unsigned* p)              { return __hip_atomic_load(p, __ATOMIC_RELAXED, __HIP_MEMORY_SCOPE_AGENT); }
; __device__ __forceinline__ unsigned xb_add(unsigned* p, unsigned v) { return __hip_atomic_fetch_add(p, v, __ATOMIC_RELAXED, __HIP_MEMORY_SCOPE_AGENT); }
; #define XB_SPIN(cond, bar) do { unsigned _sp = 0; while (cond) { __builtin_amdgcn_s_sleep(1); \
;     if ((++_sp & 255u) == 0u) { if (xb_ld(&(bar)[XB_TMO])) break; if (_sp > XB_SPIN_CAP) { atomicAdd(&(bar)[XB_TMO], 1u); break; } } } } while (0)
; __device__ __forceinline__ void xcd_barrier(const XcdBarrier& b) {
;     ...
;             if (og + 1u == (tg + 1u) * nx) xb_add(&bar[XB_TOPGEN], 1u);
;             else XB_SPIN(xb_ld(&bar[XB_TOPGEN]) == tg, bar);
;             __builtin_amdgcn_fence(__ATOMIC_ACQUIRE, "agent");
;             xb_add(&bar[XB_XGEN(b.x)], 1u);
;             asm volatile("s_waitcnt vmcnt(0)" ::: "memory");
.LBB0_352:
	s_or_b64 exec, exec, s[6:7]
.LBB0_355:
	s_or_b64 exec, exec, s[2:3]
	s_waitcnt lgkmcnt(0)
	s_barrier

; __device__ __forceinline__ unsigned xb_ld(unsigned* p)              { return __hip_atomic_load(p, __ATOMIC_RELAXED, __HIP_MEMORY_SCOPE_AGENT); }
; __device__ __forceinline__ unsigned xb_add(unsigned* p, unsigned v) { return __hip_atomic_fetch_add(p, v, __ATOMIC_RELAXED, __HIP_MEMORY_SCOPE_AGENT); }
; #define XB_SPIN(cond, bar) do { unsigned _sp = 0; while (cond) { __builtin_amdgcn_s_sleep(1); \
;     if ((++_sp & 255u) == 0u) { if (xb_ld(&(bar)[XB_TMO])) break; if (_sp > XB_SPIN_CAP) { atomicAdd(&(bar)[XB_TMO], 1u); break; } } } } while (0)
; __device__ __forceinline__ void xcd_barrier(const XcdBarrier& b) {
;     ...
;             if (og + 1u == (tg + 1u) * nx) xb_add(&bar[XB_TOPGEN], 1u);
;             else XB_SPIN(xb_ld(&bar[XB_TOPGEN]) == tg, bar);
;             __builtin_amdgcn_fence(__ATOMIC_ACQUIRE, "agent");
;             xb_add(&bar[XB_XGEN(b.x)], 1u);
;             asm volatile("s_waitcnt vmcnt(0)" ::: "memory");
.LBB0_426:
	s_or_b64 exec, exec, s[6:7]
.LBB0_429:
	s_or_b64 exec, exec, s[2:3]
	s_waitcnt lgkmcnt(0)
	s_barrier

; __device__ __forceinline__ unsigned xb_ld(unsigned* p)              { return __hip_atomic_load(p, __ATOMIC_RELAXED, __HIP_MEMORY_SCOPE_AGENT); }
; __device__ __forceinline__ unsigned xb_add(unsigned* p, unsigned v) { return __hip_atomic_fetch_add(p, v, __ATOMIC_RELAXED, __HIP_MEMORY_SCOPE_AGENT); }
; #define XB_SPIN(cond, bar) do { unsigned _sp = 0; while (cond) { __builtin_amdgcn_s_sleep(1); \
;     if ((++_sp & 255u) == 0u) { if (xb_ld(&(bar)[XB_TMO])) break; if (_sp > XB_SPIN_CAP) { atomicAdd(&(bar)[XB_TMO], 1u); break; } } } } while (0)
; __device__ __forceinline__ void xcd_barrier(const XcdBarrier& b) {
;     ...
;             if (og + 1u == (tg + 1u) * nx) xb_add(&bar[XB_TOPGEN], 1u);
;             else XB_SPIN(xb_ld(&bar[XB_TOPGEN]) == tg, bar);
;             __builtin_amdgcn_fence(__ATOMIC_ACQUIRE, "agent");
;             xb_add(&bar[XB_XGEN(b.x)], 1u);
;             asm volatile("s_waitcnt vmcnt(0)" ::: "memory");
.LBB0_506:
	s_or_b64 exec, exec, s[6:7]
.LBB0_509:
	s_or_b64 exec, exec, s[2:3]
	s_waitcnt lgkmcnt(0)
	s_barrier

; __device__ __forceinline__ unsigned xb_ld(unsigned* p)              { return __hip_atomic_load(p, __ATOMIC_RELAXED, __HIP_MEMORY_SCOPE_AGENT); }
; __device__ __forceinline__ unsigned xb_add(unsigned* p, unsigned v) { return __hip_atomic_fetch_add(p, v, __ATOMIC_RELAXED, __HIP_MEMORY_SCOPE_AGENT); }
; #define XB_SPIN(cond, bar) do { unsigned _sp = 0; while (cond) { __builtin_amdgcn_s_sleep(1); \
;     if ((++_sp & 255u) == 0u) { if (xb_ld(&(bar)[XB_TMO])) break; if (_sp > XB_SPIN_CAP) { atomicAdd(&(bar)[XB_TMO], 1u); break; } } } } while (0)
; __device__ __forceinline__ void xcd_barrier(const XcdBarrier& b) {
;     ...
;             if (og + 1u == (tg + 1u) * nx) xb_add(&bar[XB_TOPGEN], 1u);
;             else XB_SPIN(xb_ld(&bar[XB_TOPGEN]) == tg, bar);
;             __builtin_amdgcn_fence(__ATOMIC_ACQUIRE, "agent");
;             xb_add(&bar[XB_XGEN(b.x)], 1u);
;             asm volatile("s_waitcnt vmcnt(0)" ::: "memory");
.LBB0_565:
	s_or_b64 exec, exec, s[6:7]
.LBB0_568:
	s_or_b64 exec, exec, s[2:3]
	s_waitcnt lgkmcnt(0)
	s_barrier

; __device__ __forceinline__ unsigned xb_ld(unsigned* p)              { return __hip_atomic_load(p, __ATOMIC_RELAXED, __HIP_MEMORY_SCOPE_AGENT); }
; __device__ __forceinline__ unsigned xb_add(unsigned* p, unsigned v) { return __hip_atomic_fetch_add(p, v, __ATOMIC_RELAXED, __HIP_MEMORY_SCOPE_AGENT); }
; #define XB_SPIN(cond, bar) do { unsigned _sp = 0; while (cond) { __builtin_amdgcn_s_sleep(1); \
;     if ((++_sp & 255u) == 0u) { if (xb_ld(&(bar)[XB_TMO])) break; if (_sp > XB_SPIN_CAP) { atomicAdd(&(bar)[XB_TMO], 1u); break; } } } } while (0)
; __device__ __forceinline__ void xcd_barrier(const XcdBarrier& b) {
;     ...
;             if (og + 1u == (tg + 1u) * nx) xb_add(&bar[XB_TOPGEN], 1u);
;             else XB_SPIN(xb_ld(&bar[XB_TOPGEN]) == tg, bar);
;             __builtin_amdgcn_fence(__ATOMIC_ACQUIRE, "agent");
;             xb_add(&bar[XB_XGEN(b.x)], 1u);
;             asm volatile("s_waitcnt vmcnt(0)" ::: "memory");
.LBB0_658:
	s_or_b64 exec, exec, s[6:7]
.LBB0_661:
	s_or_b64 exec, exec, s[2:3]
	s_waitcnt lgkmcnt(0)
	s_barrier

; __device__ __forceinline__ unsigned xb_ld(unsigned* p)              { return __hip_atomic_load(p, __ATOMIC_RELAXED, __HIP_MEMORY_SCOPE_AGENT); }
; __device__ __forceinline__ unsigned xb_add(unsigned* p, unsigned v) { return __hip_atomic_fetch_add(p, v, __ATOMIC_RELAXED, __HIP_MEMORY_SCOPE_AGENT); }
; #define XB_SPIN(cond, bar) do { unsigned _sp = 0; while (cond) { __builtin_amdgcn_s_sleep(1); \
;     if ((++_sp & 255u) == 0u) { if (xb_ld(&(bar)[XB_TMO])) break; if (_sp > XB_SPIN_CAP) { atomicAdd(&(bar)[XB_TMO], 1u); break; } } } } while (0)
; __device__ __forceinline__ void xcd_barrier(const XcdBarrier& b) {
;     ...
;         const unsigned old = xb_add(&bar[XB_XSUB(b.x)], 1u);
;         const unsigned gen = old / nloc;
;         if (old + 1u == (gen + 1u) * nloc) {
;             __builtin_amdgcn_fence(__ATOMIC_RELEASE, "agent");
;             asm volatile("s_waitcnt vmcnt(0)" ::: "memory");
;             const unsigned og = xb_add(&bar[XB_TOP], 1u);
;             const unsigned tg = og / nx;
;             if (og + 1u == (tg + 1u) * nx) xb_add(&bar[XB_TOPGEN], 1u);
;             else XB_SPIN(xb_ld(&bar[XB_TOPGEN]) == tg, bar);
;             __builtin_amdgcn_fence(__ATOMIC_ACQUIRE, "agent");
;             xb_add(&bar[XB_XGEN(b.x)], 1u);
;             asm volatile("s_waitcnt vmcnt(0)" ::: "memory");
;         } else {
;             XB_SPIN(xb_ld(&bar[XB_XGEN(b.x)]) == gen, bar);
;             __builtin_amdgcn_fence(__ATOMIC_ACQUIRE, "agent");
;             asm volatile("s_waitcnt vmcnt(0)" ::: "memory");
;         }
.LBB0_727:
	s_or_b64 exec, exec, s[6:7]
	buffer_inv sc1
	s_waitcnt vmcnt(0)
	s_and_saveexec_b64 s[6:7], s[12:13]
	s_cbranch_execz .LBB0_729
	v_mov_b32_e32 v2, 1
	global_atomic_add v[0:1], v2, off
.LBB0_729:
	s_or_b64 exec, exec, s[6:7]
.LBB0_732:
	s_or_b64 exec, exec, s[2:3]
	s_waitcnt lgkmcnt(0)
	s_barrier

; __device__ __forceinline__ unsigned xb_ld(unsigned* p)              { return __hip_atomic_load(p, __ATOMIC_RELAXED, __HIP_MEMORY_SCOPE_AGENT); }
; __device__ __forceinline__ unsigned xb_add(unsigned* p, unsigned v) { return __hip_atomic_fetch_add(p, v, __ATOMIC_RELAXED, __HIP_MEMORY_SCOPE_AGENT); }
; #define XB_SPIN(cond, bar) do { unsigned _sp = 0; while (cond) { __builtin_amdgcn_s_sleep(1); \
;     if ((++_sp & 255u) == 0u) { if (xb_ld(&(bar)[XB_TMO])) break; if (_sp > XB_SPIN_CAP) { atomicAdd(&(bar)[XB_TMO], 1u); break; } } } } while (0)
; __device__ __forceinline__ void xcd_barrier(const XcdBarrier& b) {
;     ...
;             if (og + 1u == (tg + 1u) * nx) xb_add(&bar[XB_TOPGEN], 1u);
;             else XB_SPIN(xb_ld(&bar[XB_TOPGEN]) == tg, bar);
;             __builtin_amdgcn_fence(__ATOMIC_ACQUIRE, "agent");
;             xb_add(&bar[XB_XGEN(b.x)], 1u);
;             asm volatile("s_waitcnt vmcnt(0)" ::: "memory");
.LBB0_830:
	s_or_b64 exec, exec, s[6:7]
.LBB0_833:
	s_or_b64 exec, exec, s[2:3]
	s_waitcnt lgkmcnt(0)
	s_barrier

; __device__ __forceinline__ unsigned xb_ld(unsigned* p)              { return __hip_atomic_load(p, __ATOMIC_RELAXED, __HIP_MEMORY_SCOPE_AGENT); }
; __device__ __forceinline__ unsigned xb_add(unsigned* p, unsigned v) { return __hip_atomic_fetch_add(p, v, __ATOMIC_RELAXED, __HIP_MEMORY_SCOPE_AGENT); }
; #define XB_SPIN(cond, bar) do { unsigned _sp = 0; while (cond) { __builtin_amdgcn_s_sleep(1); \
;     if ((++_sp & 255u) == 0u) { if (xb_ld(&(bar)[XB_TMO])) break; if (_sp > XB_SPIN_CAP) { atomicAdd(&(bar)[XB_TMO], 1u); break; } } } } while (0)
; __device__ __forceinline__ void xcd_barrier(const XcdBarrier& b) {
;     ...
;             if (og + 1u == (tg + 1u) * nx) xb_add(&bar[XB_TOPGEN], 1u);
;             else XB_SPIN(xb_ld(&bar[XB_TOPGEN]) == tg, bar);
;             __builtin_amdgcn_fence(__ATOMIC_ACQUIRE, "agent");
;             xb_add(&bar[XB_XGEN(b.x)], 1u);
;             asm volatile("s_waitcnt vmcnt(0)" ::: "memory");
.LBB0_923:
	s_or_b64 exec, exec, s[6:7]
.LBB0_926:
	s_or_b64 exec, exec, s[0:1]
	s_waitcnt lgkmcnt(0)
	s_barrier

; __device__ __forceinline__ unsigned xb_ld(unsigned* p)              { return __hip_atomic_load(p, __ATOMIC_RELAXED, __HIP_MEMORY_SCOPE_AGENT); }
; __device__ __forceinline__ unsigned xb_add(unsigned* p, unsigned v) { return __hip_atomic_fetch_add(p, v, __ATOMIC_RELAXED, __HIP_MEMORY_SCOPE_AGENT); }
; #define XB_SPIN(cond, bar) do { unsigned _sp = 0; while (cond) { __builtin_amdgcn_s_sleep(1); \
;     if ((++_sp & 255u) == 0u) { if (xb_ld(&(bar)[XB_TMO])) break; if (_sp > XB_SPIN_CAP) { atomicAdd(&(bar)[XB_TMO], 1u); break; } } } } while (0)
; __device__ __forceinline__ void xcd_barrier(const XcdBarrier& b) {
;     ...
;             if (og + 1u == (tg + 1u) * nx) xb_add(&bar[XB_TOPGEN], 1u);
;             else XB_SPIN(xb_ld(&bar[XB_TOPGEN]) == tg, bar);
;             __builtin_amdgcn_fence(__ATOMIC_ACQUIRE, "agent");
;             xb_add(&bar[XB_XGEN(b.x)], 1u);
;             asm volatile("s_waitcnt vmcnt(0)" ::: "memory");
.LBB0_996:
	s_or_b64 exec, exec, s[6:7]
.LBB0_999:
	s_or_b64 exec, exec, s[0:1]
	s_waitcnt lgkmcnt(0)
	s_barrier

; __device__ __forceinline__ unsigned xb_ld(unsigned* p)              { return __hip_atomic_load(p, __ATOMIC_RELAXED, __HIP_MEMORY_SCOPE_AGENT); }
; __device__ __forceinline__ unsigned xb_add(unsigned* p, unsigned v) { return __hip_atomic_fetch_add(p, v, __ATOMIC_RELAXED, __HIP_MEMORY_SCOPE_AGENT); }
; #define XB_SPIN(cond, bar) do { unsigned _sp = 0; while (cond) { __builtin_amdgcn_s_sleep(1); \
;     if ((++_sp & 255u) == 0u) { if (xb_ld(&(bar)[XB_TMO])) break; if (_sp > XB_SPIN_CAP) { atomicAdd(&(bar)[XB_TMO], 1u); break; } } } } while (0)
; __device__ __forceinline__ void xcd_barrier(const XcdBarrier& b) {
;     ...
;             if (og + 1u == (tg + 1u) * nx) xb_add(&bar[XB_TOPGEN], 1u);
;             else XB_SPIN(xb_ld(&bar[XB_TOPGEN]) == tg, bar);
;             __builtin_amdgcn_fence(__ATOMIC_ACQUIRE, "agent");
;             xb_add(&bar[XB_XGEN(b.x)], 1u);
;             asm volatile("s_waitcnt vmcnt(0)" ::: "memory");
.LBB0_1097:
	s_or_b64 exec, exec, s[6:7]
.LBB0_1100:
	s_or_b64 exec, exec, s[2:3]
	s_waitcnt lgkmcnt(0)
	s_barrier

; __device__ __forceinline__ unsigned xb_ld(unsigned* p)              { return __hip_atomic_load(p, __ATOMIC_RELAXED, __HIP_MEMORY_SCOPE_AGENT); }
; __device__ __forceinline__ unsigned xb_add(unsigned* p, unsigned v) { return __hip_atomic_fetch_add(p, v, __ATOMIC_RELAXED, __HIP_MEMORY_SCOPE_AGENT); }
; #define XB_SPIN(cond, bar) do { unsigned _sp = 0; while (cond) { __builtin_amdgcn_s_sleep(1); \
;     if ((++_sp & 255u) == 0u) { if (xb_ld(&(bar)[XB_TMO])) break; if (_sp > XB_SPIN_CAP) { atomicAdd(&(bar)[XB_TMO], 1u); break; } } } } while (0)
; __device__ __forceinline__ void xcd_barrier(const XcdBarrier& b) {
;     ...
;             if (og + 1u == (tg + 1u) * nx) xb_add(&bar[XB_TOPGEN], 1u);
;             else XB_SPIN(xb_ld(&bar[XB_TOPGEN]) == tg, bar);
;             __builtin_amdgcn_fence(__ATOMIC_ACQUIRE, "agent");
;             xb_add(&bar[XB_XGEN(b.x)], 1u);
;             asm volatile("s_waitcnt vmcnt(0)" ::: "memory");
.LBB0_1168:
	s_or_b64 exec, exec, s[6:7]
.LBB0_1171:
	s_or_b64 exec, exec, s[2:3]
	s_waitcnt lgkmcnt(0)
	s_barrier

; __device__ __forceinline__ unsigned xb_ld(unsigned* p)              { return __hip_atomic_load(p, __ATOMIC_RELAXED, __HIP_MEMORY_SCOPE_AGENT); }
; __device__ __forceinline__ unsigned xb_add(unsigned* p, unsigned v) { return __hip_atomic_fetch_add(p, v, __ATOMIC_RELAXED, __HIP_MEMORY_SCOPE_AGENT); }
; #define XB_SPIN(cond, bar) do { unsigned _sp = 0; while (cond) { __builtin_amdgcn_s_sleep(1); \
;     if ((++_sp & 255u) == 0u) { if (xb_ld(&(bar)[XB_TMO])) break; if (_sp > XB_SPIN_CAP) { atomicAdd(&(bar)[XB_TMO], 1u); break; } } } } while (0)
; __device__ __forceinline__ void xcd_barrier(const XcdBarrier& b) {
;     ...
;             if (og + 1u == (tg + 1u) * nx) xb_add(&bar[XB_TOPGEN], 1u);
;             else XB_SPIN(xb_ld(&bar[XB_TOPGEN]) == tg, bar);
;             __builtin_amdgcn_fence(__ATOMIC_ACQUIRE, "agent");
;             xb_add(&bar[XB_XGEN(b.x)], 1u);
;             asm volatile("s_waitcnt vmcnt(0)" ::: "memory");
.LBB0_1269:
	s_or_b64 exec, exec, s[6:7]
.LBB0_1272:
	s_or_b64 exec, exec, s[2:3]
	s_waitcnt lgkmcnt(0)
	s_barrier
